# scan CUs kept quiet: the sibling half of each scanning CU runs a single a2 unit, the other a2 units go to blocks 32..255
# speedup vs baseline: 1.0280x; 1.0275x over previous
; DI void phase_m2(const Params& p, int l, int bid, int nb, h16* lds) {
;     ...
;   const int ustart = (bid < 32) ? bid : bid;
;   const int ustep = (bid < 32) ? total : (nb - 32);
;   for (int u = ustart; u < total; u += ustep) {
;     int v = u;
;     if (v >= 5288) { v -= 5288; if (v < nA) conv_one(p, l, 2560 + v, lds); else conv_one(p, l + 1, v - nA, lds); continue; }
.LBB0_892:
	s_and_b64 s[2:3], exec, s[2:3]
	s_movk_i32 s2, 0x2700
	s_cselect_b32 s91, s2, 0x5880
	v_readlane_b32 s2, v255, 30
	v_readlane_b32 s4, v255, 32
	v_readlane_b32 s3, v255, 31
	s_add_i32 s2, s4, 1
	v_readlane_b32 s5, v255, 33
	v_writelane_b32 v255, s2, 30
	s_cmp_lg_u32 s4, 3
	s_nop 0
	v_writelane_b32 v255, s3, 31
	s_cselect_b64 s[2:3], -1, 0
	v_writelane_b32 v255, s2, 36
	s_cmp_eq_u32 s4, 3
	s_nop 0
	v_writelane_b32 v255, s3, 37
	s_movk_i32 s2, 0xaa8
	s_cselect_b32 s2, s2, 0x14a8
	s_add_i32 s90, s91, s2
	v_cmp_gt_i32_e32 vcc, s90, v1
	s_and_saveexec_b64 s[64:65], vcc
	s_cbranch_execz .LBB0_1028
	v_readlane_b32 s16, v255, 32
	v_readlane_b32 s68, v255, 30
	v_readlane_b32 s2, v254, 31
	v_readlane_b32 s17, v255, 33
	v_readlane_b32 s69, v255, 31
	v_mov_b32_e32 v2, s2
	s_lshr_b32 s2, s68, 1
	s_mov_b32 s17, s69
	s_lshr_b32 s4, s16, 1
	v_readlane_b32 s36, v252, 11
	s_addk_i32 s91, 0xf600
	s_lshl_b32 s92, s16, 3
	s_mul_hi_u32 s6, s68, 0x2420000
	s_mul_i32 s7, s68, 0x2420000
	s_mul_i32 s66, s2, 0xb00000
	s_lshl_b32 s93, s2, 3
	s_lshl_b64 s[2:3], s[68:69], 22
	s_lshl_b32 s94, s4, 3
	s_mul_i32 s68, s4, 0xb00000
	s_lshl_b64 s[4:5], s[16:17], 22
	v_readlane_b32 s38, v252, 13
	v_readlane_b32 s48, v252, 23
	v_readlane_b32 s49, v252, 24
	v_readlane_b32 s50, v252, 25
	v_readlane_b32 s51, v252, 26
	v_readlane_b32 s39, v252, 14
	s_add_u32 s70, s38, s7
	v_readlane_b32 s48, v252, 43
	v_readlane_b32 s40, v252, 15
	v_readlane_b32 s41, v252, 16
	v_readlane_b32 s42, v252, 17
	v_readlane_b32 s43, v252, 18
	v_readlane_b32 s44, v252, 19
	v_readlane_b32 s45, v252, 20
	v_readlane_b32 s46, v252, 21
	v_readlane_b32 s47, v252, 22
	s_addc_u32 s71, s39, s6
	v_readlane_b32 s49, v252, 44
	v_readlane_b32 s50, v252, 45
	v_readlane_b32 s51, v252, 46
	v_readlane_b32 s52, v252, 47
	v_readlane_b32 s53, v252, 48
	v_readlane_b32 s54, v252, 49
	v_readlane_b32 s55, v252, 50
	v_readlane_b32 s56, v252, 51
	v_readlane_b32 s57, v252, 52
	s_add_u32 s72, s56, s66
	v_readlane_b32 s40, v252, 27
	s_addc_u32 s73, s57, 0
	v_readlane_b32 s50, v252, 37
	v_readlane_b32 s51, v252, 38
	s_add_u32 s74, s50, s2
	s_addc_u32 s75, s51, s3
	s_add_u32 s76, s56, s68
	s_addc_u32 s77, s57, 0
	s_add_u32 s78, s50, s4
	v_mov_b32_e32 v3, s90
	v_cmp_gt_i32_e32 vcc, 32, v1
	s_mul_hi_u32 s8, s16, 0x2420000
	v_writelane_b32 v255, s16, 32
	s_mul_i32 s9, s16, 0x2420000
	s_addc_u32 s79, s51, s5
	v_cndmask_b32_e32 v161, v2, v3, vcc
	s_add_u32 s80, s38, s9
	s_mov_b32 s67, s69
	v_writelane_b32 v255, s17, 33
	s_addc_u32 s81, s39, s8
	v_lshlrev_b32_e32 v162, 3, v1
	v_lshlrev_b32_e32 v163, 3, v161
	v_lshlrev_b32_e32 v164, 10, v1
	v_lshlrev_b32_e32 v165, 10, v161
	v_lshrrev_b32_e32 v162, 1, v181
	v_and_b32_e32 v163, 1, v181
	v_mov_b32_e32 v1, v181
	v_mov_b32_e32 v161, 0x1c0
	v_add_u32_e32 v215, 32, v162
	v_cmp_eq_u32_e32 vcc, 1, v163
	v_cndmask_b32_e32 v215, v162, v215, vcc
	v_mov_b32_e32 v165, s90
	v_cmp_gt_u32_e32 vcc, 32, v162
	v_cndmask_b32_e32 v1, v1, v215, vcc
	v_cndmask_b32_e32 v161, v161, v165, vcc
	v_lshlrev_b32_e32 v164, 10, v1
	s_mov_b64 s[82:83], 0
	v_readlane_b32 s37, v252, 12
	v_readlane_b32 s58, v252, 53
	v_readlane_b32 s59, v252, 54
	v_readlane_b32 s60, v252, 55
	v_readlane_b32 s61, v252, 56
	v_readlane_b32 s62, v252, 57
	v_readlane_b32 s63, v252, 58
	v_readlane_b32 s41, v252, 28
	v_readlane_b32 s42, v252, 29
	v_readlane_b32 s43, v252, 30
	v_readlane_b32 s44, v252, 31
	v_readlane_b32 s45, v252, 32
	v_readlane_b32 s46, v252, 33
	v_readlane_b32 s47, v252, 34
	v_readlane_b32 s48, v252, 35
	v_readlane_b32 s49, v252, 36
	v_readlane_b32 s52, v252, 39
	v_readlane_b32 s53, v252, 40
	v_readlane_b32 s54, v252, 41
	v_readlane_b32 s55, v252, 42
	s_branch .LBB0_897
